# v26 + 64-byte alignment of attention/SGU/conv loop back-edge targets
# baseline (speedup 1.0000x reference)
.LBB0_319:
	s_and_b64 s[0:1], exec, s[38:39]
	s_or_b64 s[22:23], s[0:1], s[22:23]
	s_andn2_b64 s[0:1], s[36:37], exec
	s_and_b64 s[18:19], s[48:49], exec
	s_or_b64 s[36:37], s[0:1], s[18:19]
	s_andn2_b64 exec, exec, s[22:23]
	s_cbranch_execz .LBB0_326
	.p2align	6

.LBB0_336:
	s_xor_b64 s[0:1], s[48:49], -1
	s_and_b64 s[18:19], exec, s[38:39]
	s_or_b64 s[22:23], s[18:19], s[22:23]
	s_andn2_b64 s[18:19], s[36:37], exec
	s_and_b64 s[0:1], s[0:1], exec
	s_or_b64 s[36:37], s[18:19], s[0:1]
	s_andn2_b64 exec, exec, s[22:23]
	s_cbranch_execz .LBB0_343
	.p2align	6

.LBB0_349:
	v_readlane_b32 s20, v254, 1
	s_cmp_gt_i32 s20, s8
	s_cselect_b64 s[6:7], -1, 0
	s_xor_b64 s[4:5], s[4:5], -1
	s_or_b64 s[4:5], s[6:7], s[4:5]
	s_and_b64 vcc, exec, s[4:5]
	v_readlane_b32 s21, v254, 2
	v_readlane_b32 s22, v254, 3
	v_readlane_b32 s23, v254, 4
	s_cbranch_vccnz .LBB0_415
	v_mov_b32_e32 v139, v0
	s_mov_b32 s4, 19
	s_ashr_i32 s5, s4, 31
	s_lshl_b64 s[4:5], s[4:5], 3
	v_readlane_b32 s0, v254, 7
	v_readlane_b32 s1, v254, 8
	s_add_u32 s4, s0, s4
	s_addc_u32 s5, s1, s5
	s_load_dwordx2 s[90:91], s[4:5], 0x0
	v_readlane_b32 s0, v254, 24
	v_readlane_b32 s1, v254, 25
	s_mov_b64 s[4:5], -1
	s_waitcnt lgkmcnt(0)
	s_add_u32 s52, s90, 0x23000000
	s_addc_u32 s53, s91, 0
	s_add_u32 s84, s90, 0x3b000000
	s_addc_u32 s85, s91, 0
	s_and_b64 vcc, exec, s[0:1]
	s_cbranch_vccz .LBB0_359
	s_add_u32 s4, s90, 0x2b000000
	s_mov_b32 s6, 12
	s_addc_u32 s5, s91, 0
	s_ashr_i32 s7, s6, 31
	s_lshl_b64 s[6:7], s[6:7], 3
	v_readlane_b32 s0, v254, 7
	v_readlane_b32 s1, v254, 8
	s_add_u32 s6, s0, s6
	s_addc_u32 s7, s1, s7
	s_load_dwordx2 s[6:7], s[6:7], 0x0
	v_readlane_b32 s0, v254, 27
	s_mul_i32 s80, s0, 0x1800
	s_lshl_b64 s[8:9], s[80:81], 2
	v_readlane_b32 s0, v254, 37
	s_waitcnt lgkmcnt(0)
	s_add_u32 s6, s6, s8
	s_addc_u32 s7, s7, s9
	s_add_u32 s10, s4, s0
	v_readlane_b32 s0, v254, 38
	s_addc_u32 s11, s5, s0
	v_readlane_b32 s0, v254, 39
	v_lshlrev_b32_e32 v1, 3, v139
	s_add_u32 s12, s4, s0
	v_readlane_b32 s0, v254, 40
	v_and_b32_e32 v1, 0x1f8, v1
	s_addc_u32 s13, s5, s0
	s_mov_b32 s8, 0
	.p2align	6

.LBB0_355:
	s_waitcnt vmcnt(0)
	v_mov_b32_e32 v63, v18
	v_mov_b32_e32 v65, v20
	v_mov_b32_e32 v67, v22
	v_mov_b32_e32 v69, v24
	v_mov_b32_e32 v27, v195
	v_lshl_add_u64 v[70:71], s[84:85], 0, v[26:27]
	v_mov_b32_e32 v68, v4
	v_mov_b32_e32 v24, v5
	v_mov_b32_e32 v66, v2
	v_mov_b32_e32 v22, v3
	v_mov_b32_e32 v64, v8
	v_mov_b32_e32 v20, v9
	v_mov_b32_e32 v62, v6
	v_mov_b32_e32 v18, v7
	v_mov_b32_e32 v72, v16
	v_mov_b32_e32 v73, v69
	v_mov_b32_e32 v74, v17
	v_mov_b32_e32 v75, v25
	v_mov_b32_e32 v76, v14
	v_mov_b32_e32 v77, v67
	v_mov_b32_e32 v78, v15
	v_mov_b32_e32 v79, v23
	v_mov_b32_e32 v80, v12
	v_mov_b32_e32 v81, v65
	v_mov_b32_e32 v82, v13
	v_mov_b32_e32 v83, v21
	v_mov_b32_e32 v84, v10
	v_mov_b32_e32 v85, v63
	v_mov_b32_e32 v86, v11
	v_mov_b32_e32 v87, v19
	s_mov_b32 s9, 0
	s_mov_b64 s[36:37], -1
	.p2align	6

.LBB0_362:
	s_or_b64 exec, exec, s[6:7]
	s_mov_b64 s[6:7], 0
	s_andn2_b64 vcc, exec, s[12:13]
	s_mov_b32 s27, s31
	s_mov_b32 s11, s29
	s_mov_b32 s36, s33
	s_mov_b32 s10, s50
	s_mov_b32 s51, s28
	s_cbranch_vccz .LBB0_410
	.p2align	6

.LBB0_412:
	s_waitcnt vmcnt(9)
	v_lshlrev_b64 v[34:35], 12, v[72:73]
	s_waitcnt vmcnt(4)
	s_nop 3
	v_add_f32_e32 v18, v57, v18
	s_waitcnt vmcnt(3)
	v_lshlrev_b32_e32 v36, 16, v74
	v_lshl_add_u64 v[34:35], s[84:85], 0, v[34:35]
	v_add_f32_e32 v19, v57, v19
	v_mul_f32_e32 v18, v18, v36
	v_and_b32_e32 v36, 0xffff0000, v74
	v_lshl_add_u64 v[34:35], v[34:35], 0, s[80:81]
	v_mul_f32_e32 v19, v19, v36
	v_lshl_add_u64 v[34:35], v[34:35], 0, s[78:79]
	v_add_f32_e32 v20, v57, v20
	v_cvt_pk_bf16_f32 v18, v18, v19
	v_lshlrev_b32_e32 v19, 16, v75
	v_lshl_add_u64 v[34:35], v[34:35], 0, v[194:195]
	v_add_f32_e32 v21, v57, v21
	v_mul_f32_e32 v19, v20, v19
	v_and_b32_e32 v20, 0xffff0000, v75
	v_mul_f32_e32 v20, v21, v20
	v_cvt_pk_bf16_f32 v19, v19, v20
	global_store_dwordx2 v[34:35], v[18:19], off offset:3072
	v_add_f32_e32 v18, v57, v22
	v_lshlrev_b32_e32 v22, 16, v70
	v_add_f32_e32 v19, v57, v23
	v_mul_f32_e32 v18, v18, v22
	v_and_b32_e32 v22, 0xffff0000, v70
	v_mul_f32_e32 v19, v19, v22
	v_add_f32_e32 v20, v57, v24
	v_cvt_pk_bf16_f32 v18, v18, v19
	v_lshlrev_b32_e32 v19, 16, v71
	v_add_f32_e32 v21, v57, v25
	v_mul_f32_e32 v19, v20, v19
	v_and_b32_e32 v20, 0xffff0000, v71
	v_mul_f32_e32 v20, v21, v20
	v_cvt_pk_bf16_f32 v19, v19, v20
	global_store_dwordx2 v[34:35], v[18:19], off offset:3088
	v_add_f32_e32 v18, v57, v26
	v_lshlrev_b32_e32 v22, 16, v68
	v_add_f32_e32 v19, v57, v27
	v_mul_f32_e32 v18, v18, v22
	v_and_b32_e32 v22, 0xffff0000, v68
	v_mul_f32_e32 v19, v19, v22
	v_add_f32_e32 v20, v57, v28
	v_cvt_pk_bf16_f32 v18, v18, v19
	v_lshlrev_b32_e32 v19, 16, v69
	v_add_f32_e32 v21, v57, v29
	v_mul_f32_e32 v19, v20, v19
	v_and_b32_e32 v20, 0xffff0000, v69
	v_mul_f32_e32 v20, v21, v20
	v_cvt_pk_bf16_f32 v19, v19, v20
	global_store_dwordx2 v[34:35], v[18:19], off offset:3104
	v_add_f32_e32 v18, v57, v30
	v_lshlrev_b32_e32 v22, 16, v66
	v_add_f32_e32 v19, v57, v31
	v_mul_f32_e32 v18, v18, v22
	v_and_b32_e32 v22, 0xffff0000, v66
	v_mul_f32_e32 v19, v19, v22
	v_add_f32_e32 v20, v57, v32
	v_cvt_pk_bf16_f32 v18, v18, v19
	v_lshlrev_b32_e32 v19, 16, v67
	v_add_f32_e32 v21, v57, v33
	v_mul_f32_e32 v19, v20, v19
	v_and_b32_e32 v20, 0xffff0000, v67
	v_mul_f32_e32 v20, v21, v20
	v_cvt_pk_bf16_f32 v19, v19, v20
	global_store_dwordx2 v[34:35], v[18:19], off offset:3120
	v_add_f32_e32 v2, v57, v2
	v_lshlrev_b32_e32 v18, 16, v64
	v_add_f32_e32 v3, v57, v3
	v_mul_f32_e32 v2, v2, v18
	v_and_b32_e32 v18, 0xffff0000, v64
	v_mul_f32_e32 v3, v3, v18
	v_add_f32_e32 v4, v57, v4
	v_cvt_pk_bf16_f32 v2, v2, v3
	v_lshlrev_b32_e32 v3, 16, v65
	v_add_f32_e32 v5, v57, v5
	v_mul_f32_e32 v3, v4, v3
	v_and_b32_e32 v4, 0xffff0000, v65
	v_mul_f32_e32 v4, v5, v4
	v_cvt_pk_bf16_f32 v3, v3, v4
	global_store_dwordx2 v[34:35], v[2:3], off offset:3136
	v_add_f32_e32 v2, v57, v6
	s_waitcnt vmcnt(7)
	v_lshlrev_b32_e32 v6, 16, v62
	v_add_f32_e32 v3, v57, v7
	v_mul_f32_e32 v2, v2, v6
	v_and_b32_e32 v6, 0xffff0000, v62
	v_mul_f32_e32 v3, v3, v6
	v_add_f32_e32 v4, v57, v8
	v_cvt_pk_bf16_f32 v2, v2, v3
	v_lshlrev_b32_e32 v3, 16, v63
	v_add_f32_e32 v5, v57, v9
	v_mul_f32_e32 v3, v4, v3
	v_and_b32_e32 v4, 0xffff0000, v63
	v_mul_f32_e32 v4, v5, v4
	v_cvt_pk_bf16_f32 v3, v3, v4
	global_store_dwordx2 v[34:35], v[2:3], off offset:3152
	v_add_f32_e32 v2, v57, v10
	s_waitcnt vmcnt(7)
	v_lshlrev_b32_e32 v6, 16, v60
	v_add_f32_e32 v3, v57, v11
	v_mul_f32_e32 v2, v2, v6
	v_and_b32_e32 v6, 0xffff0000, v60
	v_mul_f32_e32 v3, v3, v6
	v_add_f32_e32 v4, v57, v12
	v_cvt_pk_bf16_f32 v2, v2, v3
	v_lshlrev_b32_e32 v3, 16, v61
	v_add_f32_e32 v5, v57, v13
	v_mul_f32_e32 v3, v4, v3
	v_and_b32_e32 v4, 0xffff0000, v61
	v_mul_f32_e32 v4, v5, v4
	v_cvt_pk_bf16_f32 v3, v3, v4
	global_store_dwordx2 v[34:35], v[2:3], off offset:3168
	v_add_f32_e32 v2, v57, v14
	s_waitcnt vmcnt(7)
	v_lshlrev_b32_e32 v6, 16, v58
	v_add_f32_e32 v3, v57, v15
	v_mul_f32_e32 v2, v2, v6
	v_and_b32_e32 v6, 0xffff0000, v58
	v_readlane_b32 s0, v254, 26
	v_mul_f32_e32 v3, v3, v6
	s_add_i32 s7, s7, s0
	v_readlane_b32 s0, v254, 23
	v_add_f32_e32 v4, v57, v16
	v_cvt_pk_bf16_f32 v2, v2, v3
	v_lshlrev_b32_e32 v3, 16, v59
	s_add_i32 s8, s8, s3
	s_add_i32 s6, s6, s0
	v_add_f32_e32 v5, v57, v17
	v_mul_f32_e32 v3, v4, v3
	v_and_b32_e32 v4, 0xffff0000, v59
	s_cmpk_gt_i32 s8, 0x3ff
	v_mul_f32_e32 v4, v5, v4
	v_cvt_pk_bf16_f32 v3, v3, v4
	global_store_dwordx2 v[34:35], v[2:3], off offset:3184
	s_barrier
	s_cbranch_scc1 .LBB0_415
	.p2align	6

.LBB0_454:
	s_andn2_b64 vcc, exec, s[6:7]
	s_cbranch_vccnz .LBB0_495
	v_readlane_b32 s20, v254, 1
	s_cmp_gt_i32 s20, s9
	s_cselect_b64 s[0:1], -1, 0
	s_xor_b64 s[4:5], s[4:5], -1
	s_or_b64 s[0:1], s[0:1], s[4:5]
	s_and_b64 vcc, exec, s[0:1]
	v_readlane_b32 s21, v254, 2
	v_readlane_b32 s22, v254, 3
	v_readlane_b32 s23, v254, 4
	s_cbranch_vccnz .LBB0_458
	v_mov_b32_e32 v1, v0
	s_mov_b32 s0, 19
	s_ashr_i32 s1, s0, 31
	s_lshl_b64 s[0:1], s[0:1], 3
	v_readlane_b32 s4, v254, 7
	v_readlane_b32 s5, v254, 8
	s_add_u32 s0, s4, s0
	s_addc_u32 s1, s5, s1
	v_and_b32_e32 v2, 63, v1
	s_load_dwordx2 s[4:5], s[0:1], 0x0
	v_readlane_b32 s0, v255, 25
	v_lshlrev_b32_e32 v194, 4, v2
	v_readlane_b32 s1, v255, 26
	v_lshrrev_b32_e32 v1, 2, v1
	s_mov_b32 s6, -2
	v_lshl_add_u64 v[74:75], s[0:1], 0, v[194:195]
	v_readlane_b32 s0, v255, 17
	v_readlane_b32 s1, v255, 18
	s_nop 1
	v_lshl_add_u64 v[76:77], s[0:1], 0, v[194:195]
	v_and_b32_e32 v194, 12, v1
	v_readlane_b32 s0, v255, 19
	v_or_b32_e32 v1, 64, v2
	v_readlane_b32 s1, v255, 20
	v_lshrrev_b32_e32 v1, 2, v1
	s_nop 0
	v_lshl_add_u64 v[78:79], s[0:1], 0, v[194:195]
	v_and_b32_e32 v194, 28, v1
	v_or_b32_e32 v1, 0x80, v2
	v_lshrrev_b32_e32 v1, 2, v1
	v_lshl_add_u64 v[80:81], s[0:1], 0, v[194:195]
	v_and_b32_e32 v194, 44, v1
	v_lshl_add_u64 v[82:83], s[0:1], 0, v[194:195]
	.p2align	6

.LBB0_465:
	s_and_b64 s[0:1], exec, s[36:37]
	s_or_b64 s[12:13], s[0:1], s[12:13]
	s_andn2_b64 s[0:1], s[22:23], exec
	s_and_b64 s[18:19], s[38:39], exec
	s_or_b64 s[22:23], s[0:1], s[18:19]
	s_andn2_b64 exec, exec, s[12:13]
	s_cbranch_execz .LBB0_472
	.p2align	6

.LBB0_482:
	s_xor_b64 s[0:1], s[38:39], -1
	s_and_b64 s[18:19], exec, s[36:37]
	s_or_b64 s[12:13], s[18:19], s[12:13]
	s_andn2_b64 s[18:19], s[22:23], exec
	s_and_b64 s[0:1], s[0:1], exec
	s_or_b64 s[22:23], s[18:19], s[0:1]
	s_andn2_b64 exec, exec, s[12:13]
	s_cbranch_execz .LBB0_489
	.p2align	6

.LBB0_501:
	s_andn2_b64 vcc, exec, s[6:7]
	s_mov_b32 s57, s50
	s_mov_b32 s40, s52
	s_mov_b64 s[90:91], s[84:85]
	s_mov_b64 s[76:77], s[62:63]
	s_cbranch_vccz .LBB0_533
	.p2align	6
